# mLSTM gate pre-pass stage 1: gate loads prefetched one block ahead (on top of the shortened grid-barrier release chain)
# baseline (speedup 1.0000x reference)
.LBB0_212:
	s_lshr_b32 s0, s7, 3
	v_writelane_b32 v255, s0, 3
	s_bfe_u32 s0, s7, 0x10002
	s_bfe_u32 s21, s7, 0x30003
	v_mov_b32_e32 v0, 0x28000
	s_cmp_eq_u32 s0, 0
	v_mad_i64_i32 v[2:3], s[22:23], s7, v0, v[64:65]
	s_cselect_b64 s[92:93], -1, 0
	s_lshl_b32 s1, s7, 7
	s_and_b32 s34, s1, 0xffffe000
	s_lshl_b32 s0, s0, 5
	v_readlane_b32 s22, v254, 50
	v_readlane_b32 s23, v254, 51
	s_add_u32 s0, s22, s0
	s_addc_u32 s1, s23, 0
	s_lshl_b32 s20, s21, 2
	v_cndmask_b32_e64 v0, v87, v81, s[92:93]
	s_add_u32 s30, s0, s20
	s_mul_hi_i32 s29, s7, 0x28000
	s_mul_i32 s28, s7, 0x28000
	s_mov_b32 s4, 0
	v_or_b32_e32 v0, s34, v0
	s_addc_u32 s31, s1, 0
	v_readlane_b32 s22, v255, 0
	v_readlane_b32 s23, v255, 1
	s_waitcnt vmcnt(0)
	s_barrier
	s_and_b64 s[94:95], s[92:93], exec
	s_cselect_b32 s0, s22, s23
	v_add_u32_e32 v12, s0, v0
	v_ashrrev_i32_e32 v13, 31, v12
	v_lshlrev_b64 v[12:13], 7, v[12:13]
	v_lshl_add_u64 v[12:13], s[30:31], 0, v[12:13]
	global_load_dword v231, v[12:13], off
	global_load_dword v230, v[12:13], off offset:64
	s_waitcnt vmcnt(0)
	s_branch .LBB0_214

.LBB0_214:
	s_add_i32 s0, s22, 0x200
	s_add_i32 s1, s23, 0xfffffe00
	s_and_b64 s[94:95], s[92:93], exec
	s_cselect_b32 s0, s0, s1
	v_add_u32_e32 v12, s0, v0
	v_ashrrev_i32_e32 v13, 31, v12
	v_lshlrev_b64 v[12:13], 7, v[12:13]
	v_lshl_add_u64 v[12:13], s[30:31], 0, v[12:13]
	global_load_dword v232, v[12:13], off offset:64
	s_nop 0
	global_load_dword v233, v[12:13], off
	s_mov_b32 s0, 0x3f317217
	s_waitcnt vmcnt(5)
	v_mul_f32_e32 v12, 0xbfb8aa3b, v230
	v_exp_f32_e32 v12, v12
	s_nop 0
	v_add_f32_e32 v12, 1.0, v12
	v_cmp_gt_f32_e32 vcc, s39, v12
	s_nop 1
	v_cndmask_b32_e64 v13, 0, 32, vcc
	v_ldexp_f32 v12, v12, v13
	v_log_f32_e32 v12, v12
	s_nop 0
	v_mul_f32_e32 v13, 0x3f317217, v12
	v_fma_f32 v13, v12, s0, -v13
	v_fmac_f32_e32 v13, 0x3377d1cf, v12
	s_mov_b32 s0, 0x7f800000
	v_fmac_f32_e32 v13, 0x3f317217, v12
	v_cmp_lt_f32_e64 s[94:95], |v12|, s0
	s_nop 1
	v_cndmask_b32_e64 v12, v12, v13, s[94:95]
	v_cndmask_b32_e32 v13, 0, v213, vcc
	v_sub_f32_e32 v12, v12, v13
	v_xor_b32_e32 v13, 0x80000000, v12
	ds_bpermute_b32 v13, v117, v13
	s_waitcnt lgkmcnt(0)
	v_sub_f32_e32 v13, v13, v12
	v_cndmask_b32_e64 v12, v13, -v12, s[40:41]
	ds_bpermute_b32 v13, v118, v12
	s_waitcnt lgkmcnt(0)
	v_add_f32_e32 v13, v12, v13
	v_cndmask_b32_e64 v12, v13, v12, s[50:51]
	ds_bpermute_b32 v13, v119, v12
	s_waitcnt lgkmcnt(0)
	v_add_f32_e32 v13, v12, v13
	v_cndmask_b32_e64 v12, v13, v12, s[52:53]
	ds_bpermute_b32 v13, v120, v12
	s_waitcnt lgkmcnt(0)
	v_add_f32_e32 v13, v12, v13
	v_cndmask_b32_e64 v12, v13, v12, s[54:55]
	ds_bpermute_b32 v13, v121, v12
	s_waitcnt lgkmcnt(0)
	v_add_f32_e32 v13, v12, v13
	v_cndmask_b32_e64 v12, v13, v12, s[56:57]
	ds_bpermute_b32 v13, v122, v12
	s_waitcnt lgkmcnt(0)
	v_add_f32_e32 v13, v12, v13
	v_cndmask_b32_e64 v18, v13, v12, s[58:59]
	ds_bpermute_b32 v12, v88, v18
	s_waitcnt lgkmcnt(0)
	v_sub_f32_e32 v13, v12, v18
	v_add_f32_e32 v13, v231, v13
	v_sub_f32_e32 v15, v231, v18
	ds_bpermute_b32 v16, v117, v15
	ds_bpermute_b32 v14, v123, v13
	s_waitcnt lgkmcnt(1)
	v_max_f32_e32 v16, v16, v16
	v_max_f32_e32 v16, v15, v16
	v_cndmask_b32_e64 v16, v16, v15, s[40:41]
	ds_bpermute_b32 v17, v118, v16
	s_waitcnt lgkmcnt(1)
	v_max_f32_e32 v14, v14, v14
	v_max_f32_e32 v13, v13, v14
	ds_bpermute_b32 v14, v124, v13
	s_waitcnt lgkmcnt(1)
	v_max_f32_e32 v17, v17, v17
	v_max_f32_e32 v17, v16, v17
	v_cndmask_b32_e64 v16, v17, v16, s[50:51]
	ds_bpermute_b32 v17, v119, v16
	s_waitcnt lgkmcnt(1)
	v_max_f32_e32 v14, v14, v14
	v_max_f32_e32 v13, v13, v14
	ds_bpermute_b32 v14, v125, v13
	s_waitcnt lgkmcnt(1)
	v_max_f32_e32 v17, v17, v17
	v_max_f32_e32 v17, v16, v17
	v_cndmask_b32_e64 v16, v17, v16, s[52:53]
	ds_bpermute_b32 v17, v120, v16
	s_waitcnt lgkmcnt(1)
	v_max_f32_e32 v14, v14, v14
	v_max_f32_e32 v13, v13, v14
	ds_bpermute_b32 v14, v126, v13
	s_waitcnt lgkmcnt(1)
	v_max_f32_e32 v17, v17, v17
	v_max_f32_e32 v17, v16, v17
	v_cndmask_b32_e64 v16, v17, v16, s[54:55]
	ds_bpermute_b32 v17, v121, v16
	s_waitcnt lgkmcnt(1)
	v_max_f32_e32 v14, v14, v14
	v_max_f32_e32 v13, v13, v14
	ds_bpermute_b32 v14, v127, v13
	s_waitcnt lgkmcnt(1)
	v_max_f32_e32 v17, v17, v17
	v_max_f32_e32 v17, v16, v17
	v_cndmask_b32_e64 v16, v17, v16, s[56:57]
	ds_bpermute_b32 v17, v122, v16
	s_waitcnt lgkmcnt(1)
	v_max_f32_e32 v14, v14, v14
	v_max_f32_e32 v13, v13, v14
	ds_bpermute_b32 v14, v128, v13
	v_max_f32_e32 v19, v16, v16
	s_waitcnt lgkmcnt(1)
	v_max_f32_e32 v17, v17, v17
	v_max_f32_e32 v17, v19, v17
	v_cndmask_b32_e64 v19, v17, v16, s[58:59]
	v_add_co_u32_e32 v16, vcc, 0xffffe000, v2
	s_nop 1
	v_addc_co_u32_e32 v17, vcc, -1, v3, vcc
	global_store_dword v[16:17], v18, off offset:-3072
	global_store_dword v[16:17], v19, off offset:-2816
	global_store_dword v[16:17], v15, off offset:-2048
	s_and_saveexec_b64 s[94:95], s[40:41]
	s_cbranch_execz .LBB0_216
	s_add_i32 s0, s17, s4
	s_add_i32 s1, s0, 0x14000
	s_waitcnt lgkmcnt(0)
	v_max_f32_e32 v14, v14, v14
	v_max_f32_e32 v13, v13, v13
	s_add_i32 s0, s0, 0x14200
	v_max_f32_e32 v13, v13, v14
	v_mov_b32_e32 v14, s1
	ds_write_b32 v14, v12
	v_mov_b32_e32 v12, s0
	ds_write_b32 v12, v13
.LBB0_216:
	s_or_b64 exec, exec, s[94:95]
	s_add_i32 s0, s22, 0x400
	s_add_i32 s1, s23, 0xfffffc00
	s_and_b64 s[94:95], s[92:93], exec
	s_cselect_b32 s0, s0, s1
	v_add_u32_e32 v12, s0, v0
	v_ashrrev_i32_e32 v13, 31, v12
	v_lshlrev_b64 v[12:13], 7, v[12:13]
	v_lshl_add_u64 v[12:13], s[30:31], 0, v[12:13]
	s_waitcnt lgkmcnt(0)
	global_load_dword v231, v[12:13], off
	s_nop 0
	global_load_dword v230, v[12:13], off offset:64
	s_mov_b32 s0, 0x3f317217
	s_waitcnt vmcnt(5)
	v_mul_f32_e32 v12, 0xbfb8aa3b, v232
	v_exp_f32_e32 v12, v12
	s_nop 0
	v_add_f32_e32 v12, 1.0, v12
	v_cmp_gt_f32_e32 vcc, s39, v12
	s_nop 1
	v_cndmask_b32_e64 v14, 0, 32, vcc
	v_ldexp_f32 v12, v12, v14
	v_log_f32_e32 v12, v12
	v_cndmask_b32_e32 v14, 0, v213, vcc
	v_mul_f32_e32 v15, 0x3f317217, v12
	v_fma_f32 v15, v12, s0, -v15
	v_fmac_f32_e32 v15, 0x3377d1cf, v12
	s_mov_b32 s0, 0x7f800000
	v_fmac_f32_e32 v15, 0x3f317217, v12
	v_cmp_lt_f32_e64 vcc, |v12|, s0
	s_nop 1
	v_cndmask_b32_e32 v12, v12, v15, vcc
	v_sub_f32_e32 v12, v12, v14
	v_xor_b32_e32 v14, 0x80000000, v12
	ds_bpermute_b32 v14, v117, v14
	s_waitcnt lgkmcnt(0)
	v_sub_f32_e32 v14, v14, v12
	v_cndmask_b32_e64 v12, v14, -v12, s[40:41]
	ds_bpermute_b32 v14, v118, v12
	s_waitcnt lgkmcnt(0)
	v_add_f32_e32 v14, v12, v14
	v_cndmask_b32_e64 v12, v14, v12, s[50:51]
	ds_bpermute_b32 v14, v119, v12
	s_waitcnt lgkmcnt(0)
	v_add_f32_e32 v14, v12, v14
	v_cndmask_b32_e64 v12, v14, v12, s[52:53]
	ds_bpermute_b32 v14, v120, v12
	s_waitcnt lgkmcnt(0)
	v_add_f32_e32 v14, v12, v14
	v_cndmask_b32_e64 v12, v14, v12, s[54:55]
	ds_bpermute_b32 v14, v121, v12
	s_waitcnt lgkmcnt(0)
	v_add_f32_e32 v14, v12, v14
	v_cndmask_b32_e64 v12, v14, v12, s[56:57]
	ds_bpermute_b32 v14, v122, v12
	s_waitcnt lgkmcnt(0)
	v_add_f32_e32 v14, v12, v14
	v_cndmask_b32_e64 v14, v14, v12, s[58:59]
	s_nop 0
	v_sub_f32_e32 v15, v233, v14
	ds_bpermute_b32 v16, v117, v15
	ds_bpermute_b32 v12, v88, v14
	global_store_dword v[2:3], v14, off offset:-1024
	s_waitcnt lgkmcnt(1)
	v_max_f32_e32 v16, v16, v16
	s_waitcnt lgkmcnt(0)
	v_sub_f32_e32 v17, v12, v14
	v_max_f32_e32 v16, v15, v16
	v_add_f32_e32 v13, v233, v17
	v_cndmask_b32_e64 v16, v16, v15, s[40:41]
	ds_bpermute_b32 v17, v123, v13
	ds_bpermute_b32 v18, v118, v16
	s_waitcnt lgkmcnt(1)
	v_max_f32_e32 v17, v17, v17
	s_waitcnt lgkmcnt(0)
	v_max_f32_e32 v18, v18, v18
	v_max_f32_e32 v13, v13, v17
	v_max_f32_e32 v18, v16, v18
	ds_bpermute_b32 v17, v124, v13
	v_cndmask_b32_e64 v16, v18, v16, s[50:51]
	ds_bpermute_b32 v18, v119, v16
	s_waitcnt lgkmcnt(1)
	v_max_f32_e32 v17, v17, v17
	v_max_f32_e32 v13, v13, v17
	s_waitcnt lgkmcnt(0)
	v_max_f32_e32 v18, v18, v18
	ds_bpermute_b32 v17, v125, v13
	v_max_f32_e32 v18, v16, v18
	v_cndmask_b32_e64 v16, v18, v16, s[52:53]
	ds_bpermute_b32 v18, v120, v16
	s_waitcnt lgkmcnt(1)
	v_max_f32_e32 v17, v17, v17
	v_max_f32_e32 v13, v13, v17
	ds_bpermute_b32 v17, v126, v13
	s_waitcnt lgkmcnt(1)
	v_max_f32_e32 v18, v18, v18
	v_max_f32_e32 v18, v16, v18
	v_cndmask_b32_e64 v16, v18, v16, s[54:55]
	ds_bpermute_b32 v18, v121, v16
	s_waitcnt lgkmcnt(1)
	v_max_f32_e32 v14, v17, v17
	v_max_f32_e32 v13, v13, v14
	ds_bpermute_b32 v14, v127, v13
	s_waitcnt lgkmcnt(1)
	v_max_f32_e32 v17, v18, v18
	v_max_f32_e32 v17, v16, v17
	v_cndmask_b32_e64 v16, v17, v16, s[56:57]
	ds_bpermute_b32 v17, v122, v16
	s_waitcnt lgkmcnt(1)
	v_max_f32_e32 v14, v14, v14
	v_max_f32_e32 v13, v13, v14
	ds_bpermute_b32 v14, v128, v13
	v_max_f32_e32 v18, v16, v16
	s_waitcnt lgkmcnt(1)
	v_max_f32_e32 v17, v17, v17
	v_max_f32_e32 v17, v18, v17
	v_cndmask_b32_e64 v16, v17, v16, s[58:59]
	global_store_dword v[2:3], v16, off offset:-768
	global_store_dword v[2:3], v15, off
	s_and_saveexec_b64 s[94:95], s[40:41]
	s_cbranch_execz .LBB0_213
	s_add_i32 s0, s17, s4
	s_add_i32 s1, s0, 0x14020
	s_waitcnt lgkmcnt(0)
	v_max_f32_e32 v14, v14, v14
	v_max_f32_e32 v13, v13, v13
	s_add_i32 s0, s0, 0x14220
	v_max_f32_e32 v13, v13, v14
	v_mov_b32_e32 v14, s1
	ds_write_b32 v14, v12
	v_mov_b32_e32 v12, s0
	ds_write_b32 v12, v13
	s_branch .LBB0_213
